# combo k=2 + phase B items-first for WGs with (bid>>5)&1
# baseline (speedup 1.0000x reference)
; __global__ void __launch_bounds__(256, 2) hybrid_megakernel(Params p) {
;     ...
;     for (int vb = bid; vb < 512; vb += nb) {
;       { const int q2 = vb >> 3; inproj_tile<4>(p, l, (vb & 7) * 16 + (q2 & 15), 8 + (q2 >> 4), lds); }
;       if (vb < 64) cmp_item(p, l, vb, lds);
;       else {
;         const int j = vb - 64;
;         if (vb >= 256) { const int i2 = (vb - 256) >> 3; inproj_tile<2>(p, l, (vb & 7) * 16 + (i2 & 15), 24 + (i2 >> 4), lds); }
;         win_item(p, j, lds);
;         if (j + 448 < 512) win_item(p, j + 448, lds);
;         for (int it = j; it < 1536; it += 448) dil_item(p, it, lds);
;       }
;     }
.LBB0_213:
	s_or_b64 exec, exec, s[0:1]
	v_readlane_b32 s0, v235, 23
	v_readlane_b32 s1, v235, 24
	s_andn2_b64 vcc, exec, s[0:1]
	s_waitcnt lgkmcnt(0)
	v_cndmask_b32_e64 v0, 0, 1, s[0:1]
	v_cmp_ne_u32_e64 s[2:3], 1, v0
	s_barrier
	s_nop 0
	v_writelane_b32 v234, s2, 27
	s_nop 1
	v_writelane_b32 v234, s3, 28
	s_cbranch_vccnz .LBB0_298
	v_readlane_b32 s0, v234, 24
	s_mul_i32 s28, s0, 0xd00
	s_lshl_b32 s29, s0, 1
	v_readlane_b32 s30, v234, 18
	v_readlane_b32 s31, v234, 17
	v_readlane_b32 s34, v234, 14
	v_readlane_b32 s35, v234, 13
	v_readlane_b32 s36, v235, 0
	s_nop 1
	s_lshr_b32 s98, s36, 5
	s_and_b32 s98, s98, 1
	s_branch .LBB0_217
